# one static s_setprio 1 for the later-dispatched co-resident block (block id >= 256) during GEMM-1 and GEMM-2/3, reset to 0 after
# speedup vs baseline: 1.0070x; 1.0070x over previous
.LBB0_152:
	s_or_b64 exec, exec, s[0:1]
	s_and_b32 s0, s95, 7
	s_cmp_lg_u32 s0, 0
	s_cselect_b64 s[2:3], -1, 0
	s_lshr_b32 s8, s60, 3
	s_cmp_eq_u32 s0, 0
	s_cselect_b64 s[4:5], -1, 0
	s_and_b64 s[6:7], s[4:5], exec
	s_movk_i32 s0, 0x2c0
	s_cselect_b32 s30, s8, s60
	s_cselect_b32 s31, s0, 0x1600
	v_mov_b32_e32 v0, v208
	s_mov_b32 s1, 0
	s_cmp_ge_i32 s30, s31
	s_movk_i32 s33, 0x1600
	s_barrier
	s_cbranch_scc1 .LBB0_164
	s_mov_b32 s32, 0
	s_cmp_lt_u32 s60, 0x100
	s_cbranch_scc1 .Lprio_p1
	s_setprio 1
.Lprio_p1:
	s_lshl_b32 s6, s60, 6
	s_and_b32 s34, s6, 0x1c0
	s_lshr_b32 s0, s95, 3
	s_add_i32 s35, s34, 0xfffffd80
	s_and_b64 s[4:5], s[4:5], exec
	s_cselect_b32 s36, s0, s95
	s_add_u32 s37, s92, 0x34000000
	s_addc_u32 s38, s93, 0
	s_add_u32 s39, s92, 0x36b00000
	s_addc_u32 s40, s93, 0
	s_add_u32 s4, s92, 0x8000000
	s_addc_u32 s5, s93, 0
	s_add_u32 s6, s92, 0x8016000
	s_addc_u32 s7, s93, 0
	s_add_u32 s8, s92, 0x802c000
	s_addc_u32 s9, s93, 0
	s_add_u32 s10, s92, 0x8042000
	s_addc_u32 s11, s93, 0
	s_add_u32 s12, s92, 0x8058000
	s_addc_u32 s13, s93, 0
	s_add_u32 s14, s92, 0x806e000
	s_addc_u32 s15, s93, 0
	s_add_u32 s16, s92, 0x8084000
	s_addc_u32 s17, s93, 0
	s_add_u32 s18, s92, 0x809a000
	s_addc_u32 s19, s93, 0
	v_mov_b32_e32 v181, 0
	s_mov_b32 s41, 0x10000
	s_mov_b32 s42, 0x20000
	s_mov_b32 s43, 0x30000
	s_mov_b32 s44, 0x8000
	s_mov_b32 s45, 0x18000
	s_brev_b32 s46, 44
	s_mov_b32 s47, 0x34008000
	s_mov_b32 s48, 0x34010000
	s_mov_b32 s49, 0x34018000
	s_movk_i32 s50, 0x1000
	s_mov_b32 s51, 0x9000
	s_mov_b32 s52, 0x11000
	s_mov_b32 s53, 0x19000
	s_mov_b64 s[20:21], 0x1000
	s_mov_b64 s[22:23], 0x100
	v_mov_b32_e32 v190, 0x1600

.LBB0_164:
	s_setprio 0
	s_barrier
	v_cmp_eq_u32_e64 s[2:3], 0, v208
	s_mov_b64 s[0:1], exec
	s_nop 0
	v_writelane_b32 v254, s2, 38
	s_nop 1
	v_writelane_b32 v254, s3, 39
	s_and_b64 s[2:3], s[0:1], s[2:3]
	s_mov_b64 exec, s[2:3]
	s_cbranch_execz .LBB0_170
	s_mov_b64 s[2:3], exec
	buffer_wbl2 sc1
	s_waitcnt vmcnt(0)
	s_waitcnt vmcnt(0)
	v_mbcnt_lo_u32_b32 v0, s2, 0
	v_mbcnt_hi_u32_b32 v0, s3, v0
	v_cmp_eq_u32_e32 vcc, 0, v0
	s_and_saveexec_b64 s[4:5], vcc
	s_cbranch_execz .LBB0_167
	s_bcnt1_i32_b64 s2, s[2:3]
	v_mov_b32_e32 v1, s2
	v_readlane_b32 s2, v254, 36
	v_mov_b32_e32 v0, 0
	v_readlane_b32 s3, v254, 37
	s_nop 4
	global_atomic_add v0, v1, s[2:3]

.Lg2_entry:
	s_cmp_lt_u32 s20, 0x100
	s_cbranch_scc1 .Lprio_g2
	s_setprio 1

.Lg3_done:
	s_setprio 0
	s_waitcnt vmcnt(0)

